# v15 + branch-projection segment end: the single vmcnt(0) after the 16 merge-gate loads replaced by a counted vmcnt ladder (15..0) at each gate pair's first use
# speedup vs baseline: 1.0658x; 1.0040x over previous
.LBB0_1082:
	v_add_u32_e32 v0, v191, v227
	v_add_u32_e32 v2, v225, v226
	ds_read_b128 v[140:143], v0 offset:32768
	ds_read_b128 v[152:155], v0 offset:34816
	ds_read_b128 v[144:147], v229
	ds_read_b128 v[156:159], v230
	ds_read_b128 v[160:163], v231
	ds_read_b128 v[164:167], v2
	ds_read_b128 v[168:171], v0 offset:36864
	ds_read_b128 v[172:175], v0 offset:38912
	s_add_i32 s13, s13, 1
	s_cmp_lg_u32 s13, s51
	s_waitcnt lgkmcnt(5)
	v_mfma_f32_16x16x32_bf16 v[128:131], v[140:143], v[144:147], v[128:131]
	v_mfma_f32_16x16x32_bf16 v[124:127], v[152:155], v[144:147], v[124:127]
	s_waitcnt lgkmcnt(4)
	v_mfma_f32_16x16x32_bf16 v[112:115], v[140:143], v[156:159], v[112:115]
	v_mfma_f32_16x16x32_bf16 v[108:111], v[152:155], v[156:159], v[108:111]
	s_waitcnt lgkmcnt(1)
	v_mfma_f32_16x16x32_bf16 v[120:123], v[168:171], v[144:147], v[120:123]
	v_mfma_f32_16x16x32_bf16 v[104:107], v[168:171], v[156:159], v[104:107]
	v_mfma_f32_16x16x32_bf16 v[96:99], v[140:143], v[160:163], v[96:99]
	v_mfma_f32_16x16x32_bf16 v[92:95], v[152:155], v[160:163], v[92:95]
	s_waitcnt lgkmcnt(0)
	v_mfma_f32_16x16x32_bf16 v[116:119], v[172:175], v[144:147], v[116:119]
	v_mfma_f32_16x16x32_bf16 v[100:103], v[172:175], v[156:159], v[100:103]
	v_mfma_f32_16x16x32_bf16 v[88:91], v[168:171], v[160:163], v[88:91]
	v_mfma_f32_16x16x32_bf16 v[84:87], v[172:175], v[160:163], v[84:87]
	v_mfma_f32_16x16x32_bf16 v[80:83], v[140:143], v[164:167], v[80:83]
	v_mfma_f32_16x16x32_bf16 v[76:79], v[152:155], v[164:167], v[76:79]
	v_mfma_f32_16x16x32_bf16 v[72:75], v[168:171], v[164:167], v[72:75]
	v_mfma_f32_16x16x32_bf16 v[68:71], v[172:175], v[164:167], v[68:71]
	ds_read_b128 v[140:143], v0 offset:33792
	ds_read_b128 v[144:147], v0 offset:35840
	ds_read_b128 v[156:159], v0 offset:39936
	ds_read_b128 v[160:163], v0 offset:37888
	ds_read_b128 v[152:155], v229 offset:1024
	ds_read_b128 v[164:167], v230 offset:1024
	s_waitcnt lgkmcnt(1)
	v_mfma_f32_16x16x32_bf16 v[128:131], v[140:143], v[152:155], v[128:131]
	v_mfma_f32_16x16x32_bf16 v[124:127], v[144:147], v[152:155], v[124:127]
	v_mfma_f32_16x16x32_bf16 v[120:123], v[160:163], v[152:155], v[120:123]
	v_mfma_f32_16x16x32_bf16 v[116:119], v[156:159], v[152:155], v[116:119]
	ds_read_b128 v[152:155], v231 offset:1024
	s_waitcnt lgkmcnt(1)
	v_mfma_f32_16x16x32_bf16 v[112:115], v[140:143], v[164:167], v[112:115]
	v_mfma_f32_16x16x32_bf16 v[108:111], v[144:147], v[164:167], v[108:111]
	v_mfma_f32_16x16x32_bf16 v[104:107], v[160:163], v[164:167], v[104:107]
	v_mfma_f32_16x16x32_bf16 v[100:103], v[156:159], v[164:167], v[100:103]
	ds_read_b128 v[164:167], v2 offset:1024
	s_waitcnt lgkmcnt(1)
	v_mfma_f32_16x16x32_bf16 v[96:99], v[140:143], v[152:155], v[96:99]
	v_mfma_f32_16x16x32_bf16 v[92:95], v[144:147], v[152:155], v[92:95]
	v_mfma_f32_16x16x32_bf16 v[88:91], v[160:163], v[152:155], v[88:91]
	v_mfma_f32_16x16x32_bf16 v[84:87], v[156:159], v[152:155], v[84:87]
	s_waitcnt lgkmcnt(0)
	v_mfma_f32_16x16x32_bf16 v[80:83], v[140:143], v[164:167], v[80:83]
	v_mfma_f32_16x16x32_bf16 v[76:79], v[144:147], v[164:167], v[76:79]
	v_mfma_f32_16x16x32_bf16 v[72:75], v[160:163], v[164:167], v[72:75]
	v_mfma_f32_16x16x32_bf16 v[68:71], v[156:159], v[164:167], v[68:71]
	s_cbranch_scc1 .LBB0_1116
	s_ashr_i32 s13, s50, 2
	s_mul_i32 s13, s13, s62
	s_add_i32 s13, s13, s86
	s_mul_hi_i32 s15, s13, 0x2aaaaaab
	s_lshr_b32 s16, s15, 31
	s_ashr_i32 s15, s15, 3
	s_add_i32 s15, s15, s16
	s_mul_i32 s16, s15, 48
	v_mov_b32_e32 v0, v196
	s_sub_i32 s40, s13, s16
	s_movk_i32 s36, 0xffc0
	v_and_b32_e32 v2, 15, v0
	v_ashrrev_i32_e32 v140, 1, v0
	v_and_b32_e32 v3, 64, v0
	s_ashr_i32 s41, s40, 31
	v_and_or_b32 v2, v140, s36, v2
	v_lshrrev_b32_e32 v0, 2, v0
	s_lshl_b64 s[16:17], s[40:41], 8
	v_and_or_b32 v178, v0, 12, v3
	v_ashrrev_i32_e32 v3, 31, v2
	v_lshl_add_u64 v[140:141], s[16:17], 0, v[2:3]
	v_mov_b64_e32 v[142:143], s[30:31]
	s_and_b32 s13, s50, 3
	s_lshl_b32 s46, s15, 7
	v_mad_u64_u32 v[144:145], s[44:45], v140, s90, v[142:143]
	s_ashr_i32 s47, s46, 31
	v_mad_i32_i24 v145, v141, s90, v145
	s_lshl_b32 s36, s13, 12
	v_lshl_add_u64 v[140:141], v[144:145], 0, s[36:37]
	s_lshl_b64 s[44:45], s[46:47], 1
	v_lshl_add_u64 v[140:141], v[140:141], 0, s[44:45]
	v_lshlrev_b32_e32 v0, 1, v178
	s_mov_b32 s47, 0x114f0000
	v_lshl_add_u64 v[140:141], v[140:141], 0, v[0:1]
	s_mov_b64 s[82:83], 0x114f0800
	v_lshl_add_u64 v[144:145], v[140:141], 0, s[82:83]
	v_add_co_u32_e32 v140, vcc, s47, v140
	v_or_b32_e32 v170, 16, v2
	s_nop 0
	v_addc_co_u32_e32 v141, vcc, 0, v141, vcc
	v_ashrrev_i32_e32 v171, 31, v170
	global_load_dwordx2 v[198:199], v[140:141], off offset:2048
	global_load_dwordx2 v[180:181], v[144:145], off offset:32
	global_load_dwordx2 v[176:177], v[144:145], off offset:64
	global_load_dwordx2 v[174:175], v[144:145], off offset:96
	v_lshl_add_u64 v[140:141], s[16:17], 0, v[170:171]
	v_mad_u64_u32 v[144:145], s[48:49], v140, s90, v[142:143]
	v_mad_i32_i24 v145, v141, s90, v145
	v_lshl_add_u64 v[140:141], v[144:145], 0, s[36:37]
	v_lshl_add_u64 v[140:141], v[140:141], 0, s[44:45]
	v_lshl_add_u64 v[140:141], v[140:141], 0, v[0:1]
	v_lshl_add_u64 v[144:145], v[140:141], 0, s[82:83]
	v_add_co_u32_e32 v140, vcc, s47, v140
	v_or_b32_e32 v160, 32, v2
	s_nop 0
	v_addc_co_u32_e32 v141, vcc, 0, v141, vcc
	v_ashrrev_i32_e32 v161, 31, v160
	global_load_dwordx2 v[172:173], v[140:141], off offset:2048
	global_load_dwordx2 v[168:169], v[144:145], off offset:32
	global_load_dwordx2 v[166:167], v[144:145], off offset:64
	global_load_dwordx2 v[164:165], v[144:145], off offset:96
	v_lshl_add_u64 v[140:141], s[16:17], 0, v[160:161]
	v_mad_u64_u32 v[144:145], s[48:49], v140, s90, v[142:143]
	v_mad_i32_i24 v145, v141, s90, v145
	v_lshl_add_u64 v[140:141], v[144:145], 0, s[36:37]
	v_lshl_add_u64 v[140:141], v[140:141], 0, s[44:45]
	v_lshl_add_u64 v[140:141], v[140:141], 0, v[0:1]
	v_lshl_add_u64 v[144:145], v[140:141], 0, s[82:83]
	v_add_co_u32_e32 v140, vcc, s47, v140
	v_or_b32_e32 v148, 48, v2
	s_nop 0
	v_addc_co_u32_e32 v141, vcc, 0, v141, vcc
	v_ashrrev_i32_e32 v149, 31, v148
	global_load_dwordx2 v[162:163], v[140:141], off offset:2048
	global_load_dwordx2 v[158:159], v[144:145], off offset:32
	global_load_dwordx2 v[156:157], v[144:145], off offset:64
	global_load_dwordx2 v[154:155], v[144:145], off offset:96
	v_lshl_add_u64 v[140:141], s[16:17], 0, v[148:149]
	v_mad_u64_u32 v[142:143], s[16:17], v140, s90, v[142:143]
	v_mad_i32_i24 v143, v141, s90, v143
	v_lshl_add_u64 v[140:141], v[142:143], 0, s[36:37]
	v_lshl_add_u64 v[140:141], v[140:141], 0, s[44:45]
	v_lshl_add_u64 v[140:141], v[140:141], 0, v[0:1]
	v_lshl_add_u64 v[142:143], v[140:141], 0, s[82:83]
	v_add_co_u32_e32 v140, vcc, s47, v140
	s_nop 1
	v_addc_co_u32_e32 v141, vcc, 0, v141, vcc
	global_load_dwordx2 v[152:153], v[140:141], off offset:2048
	global_load_dwordx2 v[146:147], v[142:143], off offset:32
	global_load_dwordx2 v[144:145], v[142:143], off offset:64
	s_nop 0
	global_load_dwordx2 v[142:143], v[142:143], off offset:96
	s_waitcnt vmcnt(15)
	v_lshlrev_b32_e32 v0, 16, v198
	v_fma_f32 v28, v128, v0, v28
	v_and_b32_e32 v0, 0xffff0000, v198
	s_cmp_eq_u32 s13, 3
	v_fma_f32 v29, v129, v0, v29
	v_lshlrev_b32_e32 v0, 16, v199
	s_cselect_b64 s[48:49], -1, 0
	s_lshl_b64 s[44:45], s[40:41], 20
	v_or_b32_e32 v140, s46, v178
	v_fma_f32 v30, v130, v0, v30
	v_and_b32_e32 v0, 0xffff0000, v199
	s_cmp_lg_u32 s13, 3
	v_lshlrev_b64 v[178:179], 12, v[2:3]
	v_fmac_f32_e32 v31, v131, v0
	v_ashrrev_i32_e32 v141, 31, v140
	s_cbranch_scc1 .LBB0_1085
	s_add_u32 s16, s12, s44
	s_addc_u32 s17, s20, s45
	v_cvt_pk_bf16_f32 v2, v28, v29
	v_lshl_add_u64 v[28:29], s[16:17], 0, v[178:179]
	v_cvt_pk_bf16_f32 v3, v30, v31
	v_lshl_add_u64 v[28:29], v[140:141], 1, v[28:29]
	global_store_dwordx2 v[28:29], v[2:3], off
	v_mov_b32_e32 v2, v1
	v_mov_b32_e32 v3, v1
	v_mov_b32_e32 v0, v1
	v_mov_b64_e32 v[30:31], v[2:3]
	v_mov_b64_e32 v[28:29], v[0:1]
.LBB0_1085:
	s_waitcnt vmcnt(14)
	v_lshlrev_b32_e32 v2, 16, v180
	v_and_b32_e32 v3, 0xffff0000, v180
	v_pk_fma_f32 v[64:65], v[124:125], v[2:3], v[64:65]
	v_lshlrev_b32_e32 v2, 16, v181
	v_and_b32_e32 v3, 0xffff0000, v181
	v_cndmask_b32_e64 v0, 0, 1, s[48:49]
	v_cmp_ne_u32_e64 s[40:41], 1, v0
	s_andn2_b64 vcc, exec, s[48:49]
	v_pk_fma_f32 v[66:67], v[126:127], v[2:3], v[66:67]
	s_cbranch_vccnz .LBB0_1087
	s_add_u32 s16, s30, s44
	s_addc_u32 s17, s31, s45
	v_cvt_pk_bf16_f32 v2, v64, v65
	v_lshl_add_u64 v[64:65], s[16:17], 0, v[178:179]
	v_lshl_add_u64 v[64:65], v[140:141], 1, v[64:65]
	v_add_co_u32_e32 v64, vcc, 0x363ed000, v64
	v_cvt_pk_bf16_f32 v3, v66, v67
	s_nop 0
	v_addc_co_u32_e32 v65, vcc, 0, v65, vcc
	global_store_dwordx2 v[64:65], v[2:3], off offset:32
	v_mov_b32_e32 v2, v1
	v_mov_b32_e32 v3, v1
	v_mov_b32_e32 v0, v1
	v_mov_b64_e32 v[66:67], v[2:3]
	v_mov_b64_e32 v[64:65], v[0:1]
.LBB0_1087:
	s_waitcnt vmcnt(13)
	v_lshlrev_b32_e32 v2, 16, v176
	v_and_b32_e32 v3, 0xffff0000, v176
	v_pk_fma_f32 v[60:61], v[120:121], v[2:3], v[60:61]
	v_lshlrev_b32_e32 v2, 16, v177
	v_and_b32_e32 v3, 0xffff0000, v177
	v_readlane_b32 s48, v254, 12
	s_movk_i32 s36, 0x6000
	s_and_b64 vcc, exec, s[40:41]
	v_pk_fma_f32 v[62:63], v[122:123], v[2:3], v[62:63]
	s_cbranch_vccnz .LBB0_1089
	s_add_u32 s16, s30, s44
	s_addc_u32 s17, s31, s45
	v_cvt_pk_bf16_f32 v2, v60, v61
	v_lshl_add_u64 v[60:61], s[16:17], 0, v[178:179]
	v_lshl_add_u64 v[60:61], v[140:141], 1, v[60:61]
	v_add_co_u32_e32 v60, vcc, 0x363ed000, v60
	v_cvt_pk_bf16_f32 v3, v62, v63
	s_nop 0
	v_addc_co_u32_e32 v61, vcc, 0, v61, vcc
	global_store_dwordx2 v[60:61], v[2:3], off offset:64
	v_mov_b32_e32 v2, v1
	v_mov_b32_e32 v3, v1
	v_mov_b32_e32 v0, v1
	v_mov_b64_e32 v[62:63], v[2:3]
	v_mov_b64_e32 v[60:61], v[0:1]
.LBB0_1089:
	s_waitcnt vmcnt(12)
	v_lshlrev_b32_e32 v2, 16, v174
	v_and_b32_e32 v3, 0xffff0000, v174
	v_pk_fma_f32 v[56:57], v[116:117], v[2:3], v[56:57]
	v_lshlrev_b32_e32 v2, 16, v175
	v_and_b32_e32 v3, 0xffff0000, v175
	s_and_b64 vcc, exec, s[40:41]
	v_pk_fma_f32 v[58:59], v[118:119], v[2:3], v[58:59]
	s_cbranch_vccnz .LBB0_1091
	s_add_u32 s16, s30, s44
	s_addc_u32 s17, s31, s45
	v_cvt_pk_bf16_f32 v2, v56, v57
	v_lshl_add_u64 v[56:57], s[16:17], 0, v[178:179]
	v_lshl_add_u64 v[56:57], v[140:141], 1, v[56:57]
	v_add_co_u32_e32 v56, vcc, 0x363ed000, v56
	v_cvt_pk_bf16_f32 v3, v58, v59
	s_nop 0
	v_addc_co_u32_e32 v57, vcc, 0, v57, vcc
	global_store_dwordx2 v[56:57], v[2:3], off offset:96
	v_mov_b32_e32 v2, v1
	v_mov_b32_e32 v3, v1
	v_mov_b32_e32 v0, v1
	v_mov_b64_e32 v[58:59], v[2:3]
	v_mov_b64_e32 v[56:57], v[0:1]
.LBB0_1091:
	s_waitcnt vmcnt(11)
	v_lshlrev_b32_e32 v2, 16, v172
	v_and_b32_e32 v3, 0xffff0000, v172
	v_pk_fma_f32 v[12:13], v[112:113], v[2:3], v[12:13]
	v_lshlrev_b32_e32 v2, 16, v173
	v_and_b32_e32 v3, 0xffff0000, v173
	v_lshlrev_b64 v[116:117], 12, v[170:171]
	s_and_b64 vcc, exec, s[40:41]
	v_pk_fma_f32 v[14:15], v[114:115], v[2:3], v[14:15]
	s_cbranch_vccnz .LBB0_1093
	s_add_u32 s16, s12, s44
	s_addc_u32 s17, s20, s45
	v_cvt_pk_bf16_f32 v2, v12, v13
	v_lshl_add_u64 v[12:13], s[16:17], 0, v[116:117]
	v_cvt_pk_bf16_f32 v3, v14, v15
	v_lshl_add_u64 v[12:13], v[140:141], 1, v[12:13]
	global_store_dwordx2 v[12:13], v[2:3], off
	v_mov_b32_e32 v2, v1
	v_mov_b32_e32 v3, v1
	v_mov_b32_e32 v0, v1
	v_mov_b64_e32 v[14:15], v[2:3]
	v_mov_b64_e32 v[12:13], v[0:1]
.LBB0_1093:
	s_waitcnt vmcnt(10)
	v_lshlrev_b32_e32 v2, 16, v168
	v_and_b32_e32 v3, 0xffff0000, v168
	v_pk_fma_f32 v[52:53], v[108:109], v[2:3], v[52:53]
	v_lshlrev_b32_e32 v2, 16, v169
	v_and_b32_e32 v3, 0xffff0000, v169
	s_and_b64 vcc, exec, s[40:41]
	v_pk_fma_f32 v[54:55], v[110:111], v[2:3], v[54:55]
	s_cbranch_vccnz .LBB0_1095
	s_add_u32 s16, s30, s44
	s_addc_u32 s17, s31, s45
	v_cvt_pk_bf16_f32 v2, v52, v53
	v_lshl_add_u64 v[52:53], s[16:17], 0, v[116:117]
	v_lshl_add_u64 v[52:53], v[140:141], 1, v[52:53]
	v_add_co_u32_e32 v52, vcc, 0x363ed000, v52
	v_cvt_pk_bf16_f32 v3, v54, v55
	s_nop 0
	v_addc_co_u32_e32 v53, vcc, 0, v53, vcc
	global_store_dwordx2 v[52:53], v[2:3], off offset:32
	v_mov_b32_e32 v2, v1
	v_mov_b32_e32 v3, v1
	v_mov_b32_e32 v0, v1
	v_mov_b64_e32 v[54:55], v[2:3]
	v_mov_b64_e32 v[52:53], v[0:1]
.LBB0_1095:
	s_waitcnt vmcnt(9)
	v_lshlrev_b32_e32 v2, 16, v166
	v_and_b32_e32 v3, 0xffff0000, v166
	v_pk_fma_f32 v[48:49], v[104:105], v[2:3], v[48:49]
	v_lshlrev_b32_e32 v2, 16, v167
	v_and_b32_e32 v3, 0xffff0000, v167
	s_and_b64 vcc, exec, s[40:41]
	v_pk_fma_f32 v[50:51], v[106:107], v[2:3], v[50:51]
	s_cbranch_vccnz .LBB0_1097
	s_add_u32 s16, s30, s44
	s_addc_u32 s17, s31, s45
	v_cvt_pk_bf16_f32 v2, v48, v49
	v_lshl_add_u64 v[48:49], s[16:17], 0, v[116:117]
	v_lshl_add_u64 v[48:49], v[140:141], 1, v[48:49]
	v_add_co_u32_e32 v48, vcc, 0x363ed000, v48
	v_cvt_pk_bf16_f32 v3, v50, v51
	s_nop 0
	v_addc_co_u32_e32 v49, vcc, 0, v49, vcc
	global_store_dwordx2 v[48:49], v[2:3], off offset:64
	v_mov_b32_e32 v2, v1
	v_mov_b32_e32 v3, v1
	v_mov_b32_e32 v0, v1
	v_mov_b64_e32 v[50:51], v[2:3]
	v_mov_b64_e32 v[48:49], v[0:1]
.LBB0_1097:
	s_waitcnt vmcnt(8)
	v_lshlrev_b32_e32 v2, 16, v164
	v_and_b32_e32 v3, 0xffff0000, v164
	v_pk_fma_f32 v[44:45], v[100:101], v[2:3], v[44:45]
	v_lshlrev_b32_e32 v2, 16, v165
	v_and_b32_e32 v3, 0xffff0000, v165
	s_and_b64 vcc, exec, s[40:41]
	v_pk_fma_f32 v[46:47], v[102:103], v[2:3], v[46:47]
	s_cbranch_vccnz .LBB0_1099
	s_add_u32 s16, s30, s44
	s_addc_u32 s17, s31, s45
	v_cvt_pk_bf16_f32 v2, v44, v45
	v_lshl_add_u64 v[44:45], s[16:17], 0, v[116:117]
	v_lshl_add_u64 v[44:45], v[140:141], 1, v[44:45]
	v_add_co_u32_e32 v44, vcc, 0x363ed000, v44
	v_cvt_pk_bf16_f32 v3, v46, v47
	s_nop 0
	v_addc_co_u32_e32 v45, vcc, 0, v45, vcc
	global_store_dwordx2 v[44:45], v[2:3], off offset:96
	v_mov_b32_e32 v2, v1
	v_mov_b32_e32 v3, v1
	v_mov_b32_e32 v0, v1
	v_mov_b64_e32 v[46:47], v[2:3]
	v_mov_b64_e32 v[44:45], v[0:1]
.LBB0_1099:
	s_waitcnt vmcnt(7)
	v_lshlrev_b32_e32 v2, 16, v162
	v_and_b32_e32 v3, 0xffff0000, v162
	v_pk_fma_f32 v[8:9], v[96:97], v[2:3], v[8:9]
	v_lshlrev_b32_e32 v2, 16, v163
	v_and_b32_e32 v3, 0xffff0000, v163
	v_lshlrev_b64 v[100:101], 12, v[160:161]
	s_and_b64 vcc, exec, s[40:41]
	v_pk_fma_f32 v[10:11], v[98:99], v[2:3], v[10:11]
	s_cbranch_vccnz .LBB0_1101
	s_add_u32 s16, s12, s44
	s_addc_u32 s17, s20, s45
	v_cvt_pk_bf16_f32 v2, v8, v9
	v_lshl_add_u64 v[8:9], s[16:17], 0, v[100:101]
	v_cvt_pk_bf16_f32 v3, v10, v11
	v_lshl_add_u64 v[8:9], v[140:141], 1, v[8:9]
	global_store_dwordx2 v[8:9], v[2:3], off
	v_mov_b32_e32 v2, v1
	v_mov_b32_e32 v3, v1
	v_mov_b32_e32 v0, v1
	v_mov_b64_e32 v[10:11], v[2:3]
	v_mov_b64_e32 v[8:9], v[0:1]
.LBB0_1101:
	s_waitcnt vmcnt(6)
	v_lshlrev_b32_e32 v2, 16, v158
	v_and_b32_e32 v3, 0xffff0000, v158
	v_pk_fma_f32 v[40:41], v[92:93], v[2:3], v[40:41]
	v_lshlrev_b32_e32 v2, 16, v159
	v_and_b32_e32 v3, 0xffff0000, v159
	s_and_b64 vcc, exec, s[40:41]
	v_pk_fma_f32 v[42:43], v[94:95], v[2:3], v[42:43]
	s_cbranch_vccnz .LBB0_1103
	s_add_u32 s16, s30, s44
	s_addc_u32 s17, s31, s45
	v_cvt_pk_bf16_f32 v2, v40, v41
	v_lshl_add_u64 v[40:41], s[16:17], 0, v[100:101]
	v_lshl_add_u64 v[40:41], v[140:141], 1, v[40:41]
	v_add_co_u32_e32 v40, vcc, 0x363ed000, v40
	v_cvt_pk_bf16_f32 v3, v42, v43
	s_nop 0
	v_addc_co_u32_e32 v41, vcc, 0, v41, vcc
	global_store_dwordx2 v[40:41], v[2:3], off offset:32
	v_mov_b32_e32 v2, v1
	v_mov_b32_e32 v3, v1
	v_mov_b32_e32 v0, v1
	v_mov_b64_e32 v[42:43], v[2:3]
	v_mov_b64_e32 v[40:41], v[0:1]
.LBB0_1103:
	s_waitcnt vmcnt(5)
	v_lshlrev_b32_e32 v2, 16, v156
	v_and_b32_e32 v3, 0xffff0000, v156
	v_pk_fma_f32 v[36:37], v[88:89], v[2:3], v[36:37]
	v_lshlrev_b32_e32 v2, 16, v157
	v_and_b32_e32 v3, 0xffff0000, v157
	s_and_b64 vcc, exec, s[40:41]
	v_pk_fma_f32 v[38:39], v[90:91], v[2:3], v[38:39]
	s_cbranch_vccnz .LBB0_1105
	s_add_u32 s16, s30, s44
	s_addc_u32 s17, s31, s45
	v_cvt_pk_bf16_f32 v2, v36, v37
	v_lshl_add_u64 v[36:37], s[16:17], 0, v[100:101]
	v_lshl_add_u64 v[36:37], v[140:141], 1, v[36:37]
	v_add_co_u32_e32 v36, vcc, 0x363ed000, v36
	v_cvt_pk_bf16_f32 v3, v38, v39
	s_nop 0
	v_addc_co_u32_e32 v37, vcc, 0, v37, vcc
	global_store_dwordx2 v[36:37], v[2:3], off offset:64
	v_mov_b32_e32 v2, v1
	v_mov_b32_e32 v3, v1
	v_mov_b32_e32 v0, v1
	v_mov_b64_e32 v[38:39], v[2:3]
	v_mov_b64_e32 v[36:37], v[0:1]
.LBB0_1105:
	s_waitcnt vmcnt(4)
	v_lshlrev_b32_e32 v2, 16, v154
	v_and_b32_e32 v3, 0xffff0000, v154
	v_pk_fma_f32 v[32:33], v[84:85], v[2:3], v[32:33]
	v_lshlrev_b32_e32 v2, 16, v155
	v_and_b32_e32 v3, 0xffff0000, v155
	s_and_b64 vcc, exec, s[40:41]
	v_pk_fma_f32 v[34:35], v[86:87], v[2:3], v[34:35]
	s_cbranch_vccnz .LBB0_1107
	s_add_u32 s16, s30, s44
	s_addc_u32 s17, s31, s45
	v_cvt_pk_bf16_f32 v2, v32, v33
	v_lshl_add_u64 v[32:33], s[16:17], 0, v[100:101]
	v_lshl_add_u64 v[32:33], v[140:141], 1, v[32:33]
	v_add_co_u32_e32 v32, vcc, 0x363ed000, v32
	v_cvt_pk_bf16_f32 v3, v34, v35
	s_nop 0
	v_addc_co_u32_e32 v33, vcc, 0, v33, vcc
	global_store_dwordx2 v[32:33], v[2:3], off offset:96
	v_mov_b32_e32 v2, v1
	v_mov_b32_e32 v3, v1
	v_mov_b32_e32 v0, v1
	v_mov_b64_e32 v[34:35], v[2:3]
	v_mov_b64_e32 v[32:33], v[0:1]
.LBB0_1107:
	s_waitcnt vmcnt(3)
	v_lshlrev_b32_e32 v2, 16, v152
	v_and_b32_e32 v3, 0xffff0000, v152
	v_pk_fma_f32 v[4:5], v[80:81], v[2:3], v[4:5]
	v_lshlrev_b32_e32 v2, 16, v153
	v_and_b32_e32 v3, 0xffff0000, v153
	v_lshlrev_b64 v[84:85], 12, v[148:149]
	s_and_b64 vcc, exec, s[40:41]
	v_pk_fma_f32 v[6:7], v[82:83], v[2:3], v[6:7]
	s_cbranch_vccnz .LBB0_1109
	s_add_u32 s16, s12, s44
	s_addc_u32 s17, s20, s45
	v_cvt_pk_bf16_f32 v2, v4, v5
	v_lshl_add_u64 v[4:5], s[16:17], 0, v[84:85]
	v_cvt_pk_bf16_f32 v3, v6, v7
	v_lshl_add_u64 v[4:5], v[140:141], 1, v[4:5]
	global_store_dwordx2 v[4:5], v[2:3], off
	v_mov_b32_e32 v2, v1
	v_mov_b32_e32 v3, v1
	v_mov_b32_e32 v0, v1
	v_mov_b64_e32 v[6:7], v[2:3]
	v_mov_b64_e32 v[4:5], v[0:1]
.LBB0_1109:
	s_waitcnt vmcnt(2)
	v_lshlrev_b32_e32 v2, 16, v146
	v_and_b32_e32 v3, 0xffff0000, v146
	v_pk_fma_f32 v[24:25], v[76:77], v[2:3], v[24:25]
	v_lshlrev_b32_e32 v2, 16, v147
	v_and_b32_e32 v3, 0xffff0000, v147
	s_and_b64 vcc, exec, s[40:41]
	v_pk_fma_f32 v[26:27], v[78:79], v[2:3], v[26:27]
	s_cbranch_vccnz .LBB0_1111
	s_add_u32 s16, s30, s44
	s_addc_u32 s17, s31, s45
	v_cvt_pk_bf16_f32 v2, v24, v25
	v_lshl_add_u64 v[24:25], s[16:17], 0, v[84:85]
	v_lshl_add_u64 v[24:25], v[140:141], 1, v[24:25]
	v_add_co_u32_e32 v24, vcc, 0x363ed000, v24
	v_cvt_pk_bf16_f32 v3, v26, v27
	s_nop 0
	v_addc_co_u32_e32 v25, vcc, 0, v25, vcc
	global_store_dwordx2 v[24:25], v[2:3], off offset:32
	v_mov_b32_e32 v2, v1
	v_mov_b32_e32 v3, v1
	v_mov_b32_e32 v0, v1
	v_mov_b64_e32 v[26:27], v[2:3]
	v_mov_b64_e32 v[24:25], v[0:1]
.LBB0_1111:
	s_waitcnt vmcnt(1)
	v_lshlrev_b32_e32 v2, 16, v144
	v_and_b32_e32 v3, 0xffff0000, v144
	v_pk_fma_f32 v[20:21], v[72:73], v[2:3], v[20:21]
	v_lshlrev_b32_e32 v2, 16, v145
	v_and_b32_e32 v3, 0xffff0000, v145
	s_and_b64 vcc, exec, s[40:41]
	v_pk_fma_f32 v[22:23], v[74:75], v[2:3], v[22:23]
	s_cbranch_vccnz .LBB0_1113
	s_add_u32 s16, s30, s44
	s_addc_u32 s17, s31, s45
	v_cvt_pk_bf16_f32 v2, v20, v21
	v_lshl_add_u64 v[20:21], s[16:17], 0, v[84:85]
	v_lshl_add_u64 v[20:21], v[140:141], 1, v[20:21]
	v_add_co_u32_e32 v20, vcc, 0x363ed000, v20
	v_cvt_pk_bf16_f32 v3, v22, v23
	s_nop 0
	v_addc_co_u32_e32 v21, vcc, 0, v21, vcc
	global_store_dwordx2 v[20:21], v[2:3], off offset:64
	v_mov_b32_e32 v2, v1
	v_mov_b32_e32 v3, v1
	v_mov_b32_e32 v0, v1
	v_mov_b64_e32 v[22:23], v[2:3]
	v_mov_b64_e32 v[20:21], v[0:1]
.LBB0_1113:
	s_waitcnt vmcnt(0)
	v_lshlrev_b32_e32 v2, 16, v142
	v_and_b32_e32 v3, 0xffff0000, v142
	v_pk_fma_f32 v[16:17], v[68:69], v[2:3], v[16:17]
	v_lshlrev_b32_e32 v2, 16, v143
	v_and_b32_e32 v3, 0xffff0000, v143
	s_and_b64 vcc, exec, s[40:41]
	v_pk_fma_f32 v[18:19], v[70:71], v[2:3], v[18:19]
	s_cbranch_vccnz .LBB0_1115
	s_add_u32 s16, s30, s44
	s_addc_u32 s17, s31, s45
	v_cvt_pk_bf16_f32 v2, v16, v17
	v_lshl_add_u64 v[16:17], s[16:17], 0, v[84:85]
	v_lshl_add_u64 v[16:17], v[140:141], 1, v[16:17]
	v_add_co_u32_e32 v16, vcc, 0x363ed000, v16
	v_cvt_pk_bf16_f32 v3, v18, v19
	s_nop 0
	v_addc_co_u32_e32 v17, vcc, 0, v17, vcc
	global_store_dwordx2 v[16:17], v[2:3], off offset:96
	v_mov_b32_e32 v2, v1
	v_mov_b32_e32 v3, v1
	v_mov_b32_e32 v0, v1
	v_mov_b64_e32 v[18:19], v[2:3]
	v_mov_b64_e32 v[16:17], v[0:1]

.LBB0_1128:
	v_add_u32_e32 v0, v228, v224
	ds_read_b128 v[140:143], v235
	ds_read_b128 v[152:155], v235 offset:2048
	ds_read_b128 v[144:147], v232
	ds_read_b128 v[164:167], v0
	ds_read_b128 v[156:159], v233
	ds_read_b128 v[160:163], v234
	ds_read_b128 v[168:171], v235 offset:4096
	ds_read_b128 v[172:175], v235 offset:6144
	s_add_i32 s13, s13, 1
	s_cmp_lg_u32 s13, s51
	s_waitcnt lgkmcnt(5)
	v_mfma_f32_16x16x32_bf16 v[128:131], v[140:143], v[144:147], v[128:131]
	v_mfma_f32_16x16x32_bf16 v[124:127], v[152:155], v[144:147], v[124:127]
	s_waitcnt lgkmcnt(4)
	v_mfma_f32_16x16x32_bf16 v[112:115], v[140:143], v[164:167], v[112:115]
	v_mfma_f32_16x16x32_bf16 v[108:111], v[152:155], v[164:167], v[108:111]
	s_waitcnt lgkmcnt(1)
	v_mfma_f32_16x16x32_bf16 v[120:123], v[168:171], v[144:147], v[120:123]
	v_mfma_f32_16x16x32_bf16 v[104:107], v[168:171], v[164:167], v[104:107]
	v_mfma_f32_16x16x32_bf16 v[96:99], v[140:143], v[156:159], v[96:99]
	v_mfma_f32_16x16x32_bf16 v[92:95], v[152:155], v[156:159], v[92:95]
	s_waitcnt lgkmcnt(0)
	v_mfma_f32_16x16x32_bf16 v[116:119], v[172:175], v[144:147], v[116:119]
	v_mfma_f32_16x16x32_bf16 v[100:103], v[172:175], v[164:167], v[100:103]
	v_mfma_f32_16x16x32_bf16 v[88:91], v[168:171], v[156:159], v[88:91]
	v_mfma_f32_16x16x32_bf16 v[84:87], v[172:175], v[156:159], v[84:87]
	v_mfma_f32_16x16x32_bf16 v[80:83], v[140:143], v[160:163], v[80:83]
	v_mfma_f32_16x16x32_bf16 v[76:79], v[152:155], v[160:163], v[76:79]
	v_mfma_f32_16x16x32_bf16 v[72:75], v[168:171], v[160:163], v[72:75]
	v_mfma_f32_16x16x32_bf16 v[68:71], v[172:175], v[160:163], v[68:71]
	ds_read_b128 v[140:143], v235 offset:1024
	ds_read_b128 v[144:147], v235 offset:3072
	ds_read_b128 v[156:159], v235 offset:7168
	ds_read_b128 v[160:163], v235 offset:5120
	ds_read_b128 v[152:155], v233 offset:1024
	ds_read_b128 v[164:167], v234 offset:1024
	s_waitcnt lgkmcnt(1)
	v_mfma_f32_16x16x32_bf16 v[96:99], v[140:143], v[152:155], v[96:99]
	v_mfma_f32_16x16x32_bf16 v[92:95], v[144:147], v[152:155], v[92:95]
	v_mfma_f32_16x16x32_bf16 v[88:91], v[160:163], v[152:155], v[88:91]
	v_mfma_f32_16x16x32_bf16 v[84:87], v[156:159], v[152:155], v[84:87]
	ds_read_b128 v[152:155], v0 offset:1024
	s_waitcnt lgkmcnt(0)
	v_mfma_f32_16x16x32_bf16 v[112:115], v[140:143], v[152:155], v[112:115]
	v_mfma_f32_16x16x32_bf16 v[108:111], v[144:147], v[152:155], v[108:111]
	v_mfma_f32_16x16x32_bf16 v[104:107], v[160:163], v[152:155], v[104:107]
	v_mfma_f32_16x16x32_bf16 v[100:103], v[156:159], v[152:155], v[100:103]
	ds_read_b128 v[152:155], v232 offset:1024
	s_waitcnt lgkmcnt(0)
	v_mfma_f32_16x16x32_bf16 v[128:131], v[140:143], v[152:155], v[128:131]
	v_mfma_f32_16x16x32_bf16 v[124:127], v[144:147], v[152:155], v[124:127]
	v_mfma_f32_16x16x32_bf16 v[120:123], v[160:163], v[152:155], v[120:123]
	v_mfma_f32_16x16x32_bf16 v[116:119], v[156:159], v[152:155], v[116:119]
	v_mfma_f32_16x16x32_bf16 v[80:83], v[140:143], v[164:167], v[80:83]
	v_mfma_f32_16x16x32_bf16 v[76:79], v[144:147], v[164:167], v[76:79]
	v_mfma_f32_16x16x32_bf16 v[72:75], v[160:163], v[164:167], v[72:75]
	v_mfma_f32_16x16x32_bf16 v[68:71], v[156:159], v[164:167], v[68:71]
	s_cbranch_scc1 .LBB0_1162
	s_ashr_i32 s6, s50, 2
	s_mul_i32 s6, s6, s62
	s_add_i32 s6, s6, s86
	s_mul_hi_i32 s7, s6, 0x2aaaaaab
	s_lshr_b32 s13, s7, 31
	s_ashr_i32 s7, s7, 3
	s_add_i32 s13, s7, s13
	s_mul_i32 s7, s13, 48
	v_mov_b32_e32 v0, v196
	s_sub_i32 s6, s6, s7
	s_movk_i32 s16, 0xffc0
	v_and_b32_e32 v2, 15, v0
	v_ashrrev_i32_e32 v140, 1, v0
	v_and_b32_e32 v3, 64, v0
	s_ashr_i32 s7, s6, 31
	v_and_or_b32 v2, v140, s16, v2
	v_lshrrev_b32_e32 v0, 2, v0
	s_lshl_b64 s[14:15], s[6:7], 8
	v_and_or_b32 v178, v0, 12, v3
	v_ashrrev_i32_e32 v3, 31, v2
	v_lshl_add_u64 v[140:141], s[14:15], 0, v[2:3]
	v_mov_b64_e32 v[142:143], s[30:31]
	s_and_b32 s46, s50, 3
	s_lshl_b32 s40, s13, 7
	v_mad_u64_u32 v[144:145], s[16:17], v140, s90, v[142:143]
	s_ashr_i32 s41, s40, 31
	v_mad_i32_i24 v145, v141, s90, v145
	s_lshl_b32 s36, s46, 12
	v_lshl_add_u64 v[140:141], v[144:145], 0, s[36:37]
	s_lshl_b64 s[16:17], s[40:41], 1
	v_lshl_add_u64 v[140:141], v[140:141], 0, s[16:17]
	v_lshlrev_b32_e32 v0, 1, v178
	v_lshl_add_u64 v[140:141], v[140:141], 0, v[0:1]
	s_mov_b64 s[82:83], 0x114f0800
	v_lshl_add_u64 v[144:145], v[140:141], 0, s[82:83]
	v_add_co_u32_e32 v140, vcc, s47, v140
	v_or_b32_e32 v170, 16, v2
	s_nop 0
	v_addc_co_u32_e32 v141, vcc, 0, v141, vcc
	v_ashrrev_i32_e32 v171, 31, v170
	global_load_dwordx2 v[198:199], v[140:141], off offset:2048
	global_load_dwordx2 v[180:181], v[144:145], off offset:32
	global_load_dwordx2 v[176:177], v[144:145], off offset:64
	global_load_dwordx2 v[174:175], v[144:145], off offset:96
	v_lshl_add_u64 v[140:141], s[14:15], 0, v[170:171]
	v_mad_u64_u32 v[144:145], s[44:45], v140, s90, v[142:143]
	v_mad_i32_i24 v145, v141, s90, v145
	v_lshl_add_u64 v[140:141], v[144:145], 0, s[36:37]
	v_lshl_add_u64 v[140:141], v[140:141], 0, s[16:17]
	v_lshl_add_u64 v[140:141], v[140:141], 0, v[0:1]
	v_lshl_add_u64 v[144:145], v[140:141], 0, s[82:83]
	v_add_co_u32_e32 v140, vcc, s47, v140
	v_or_b32_e32 v160, 32, v2
	s_nop 0
	v_addc_co_u32_e32 v141, vcc, 0, v141, vcc
	v_ashrrev_i32_e32 v161, 31, v160
	global_load_dwordx2 v[172:173], v[140:141], off offset:2048
	global_load_dwordx2 v[168:169], v[144:145], off offset:32
	global_load_dwordx2 v[166:167], v[144:145], off offset:64
	global_load_dwordx2 v[164:165], v[144:145], off offset:96
	v_lshl_add_u64 v[140:141], s[14:15], 0, v[160:161]
	v_mad_u64_u32 v[144:145], s[44:45], v140, s90, v[142:143]
	v_mad_i32_i24 v145, v141, s90, v145
	v_lshl_add_u64 v[140:141], v[144:145], 0, s[36:37]
	v_lshl_add_u64 v[140:141], v[140:141], 0, s[16:17]
	v_lshl_add_u64 v[140:141], v[140:141], 0, v[0:1]
	v_lshl_add_u64 v[144:145], v[140:141], 0, s[82:83]
	v_add_co_u32_e32 v140, vcc, s47, v140
	v_or_b32_e32 v148, 48, v2
	s_nop 0
	v_addc_co_u32_e32 v141, vcc, 0, v141, vcc
	v_ashrrev_i32_e32 v149, 31, v148
	global_load_dwordx2 v[162:163], v[140:141], off offset:2048
	global_load_dwordx2 v[158:159], v[144:145], off offset:32
	global_load_dwordx2 v[156:157], v[144:145], off offset:64
	global_load_dwordx2 v[154:155], v[144:145], off offset:96
	v_lshl_add_u64 v[140:141], s[14:15], 0, v[148:149]
	v_mad_u64_u32 v[142:143], s[14:15], v140, s90, v[142:143]
	v_mad_i32_i24 v143, v141, s90, v143
	v_lshl_add_u64 v[140:141], v[142:143], 0, s[36:37]
	v_lshl_add_u64 v[140:141], v[140:141], 0, s[16:17]
	v_lshl_add_u64 v[140:141], v[140:141], 0, v[0:1]
	v_lshl_add_u64 v[142:143], v[140:141], 0, s[82:83]
	v_add_co_u32_e32 v140, vcc, s47, v140
	s_nop 1
	v_addc_co_u32_e32 v141, vcc, 0, v141, vcc
	global_load_dwordx2 v[152:153], v[140:141], off offset:2048
	global_load_dwordx2 v[146:147], v[142:143], off offset:32
	global_load_dwordx2 v[144:145], v[142:143], off offset:64
	s_nop 0
	global_load_dwordx2 v[142:143], v[142:143], off offset:96
	s_waitcnt vmcnt(15)
	v_lshlrev_b32_e32 v0, 16, v198
	v_fma_f32 v28, v128, v0, v28
	v_and_b32_e32 v0, 0xffff0000, v198
	s_cmp_eq_u32 s46, 3
	v_fma_f32 v29, v129, v0, v29
	v_lshlrev_b32_e32 v0, 16, v199
	s_cselect_b64 s[44:45], -1, 0
	s_lshl_b64 s[6:7], s[6:7], 20
	v_or_b32_e32 v140, s40, v178
	v_fma_f32 v30, v130, v0, v30
	v_and_b32_e32 v0, 0xffff0000, v199
	s_cmp_lg_u32 s46, 3
	v_lshlrev_b64 v[178:179], 12, v[2:3]
	v_fmac_f32_e32 v31, v131, v0
	v_ashrrev_i32_e32 v141, 31, v140
	s_cbranch_scc1 .LBB0_1131
	s_add_u32 s14, s12, s6
	s_addc_u32 s15, s20, s7
	v_cvt_pk_bf16_f32 v2, v28, v29
	v_lshl_add_u64 v[28:29], s[14:15], 0, v[178:179]
	v_cvt_pk_bf16_f32 v3, v30, v31
	v_lshl_add_u64 v[28:29], v[140:141], 1, v[28:29]
	global_store_dwordx2 v[28:29], v[2:3], off
	v_mov_b32_e32 v2, v1
	v_mov_b32_e32 v3, v1
	v_mov_b32_e32 v0, v1
	v_mov_b64_e32 v[30:31], v[2:3]
	v_mov_b64_e32 v[28:29], v[0:1]
.LBB0_1131:
	s_waitcnt vmcnt(14)
	v_lshlrev_b32_e32 v2, 16, v180
	v_and_b32_e32 v3, 0xffff0000, v180
	v_pk_fma_f32 v[64:65], v[124:125], v[2:3], v[64:65]
	v_lshlrev_b32_e32 v2, 16, v181
	v_and_b32_e32 v3, 0xffff0000, v181
	v_cndmask_b32_e64 v0, 0, 1, s[44:45]
	v_cmp_ne_u32_e64 s[40:41], 1, v0
	s_andn2_b64 vcc, exec, s[44:45]
	v_pk_fma_f32 v[66:67], v[126:127], v[2:3], v[66:67]
	s_cbranch_vccnz .LBB0_1133
	s_add_u32 s14, s30, s6
	s_addc_u32 s15, s31, s7
	v_cvt_pk_bf16_f32 v2, v64, v65
	v_lshl_add_u64 v[64:65], s[14:15], 0, v[178:179]
	v_lshl_add_u64 v[64:65], v[140:141], 1, v[64:65]
	v_add_co_u32_e32 v64, vcc, 0x363ed000, v64
	v_cvt_pk_bf16_f32 v3, v66, v67
	s_nop 0
	v_addc_co_u32_e32 v65, vcc, 0, v65, vcc
	global_store_dwordx2 v[64:65], v[2:3], off offset:32
	v_mov_b32_e32 v2, v1
	v_mov_b32_e32 v3, v1
	v_mov_b32_e32 v0, v1
	v_mov_b64_e32 v[66:67], v[2:3]
	v_mov_b64_e32 v[64:65], v[0:1]
.LBB0_1133:
	s_waitcnt vmcnt(13)
	v_lshlrev_b32_e32 v2, 16, v176
	v_and_b32_e32 v3, 0xffff0000, v176
	v_readlane_b32 s44, v254, 53
	v_pk_fma_f32 v[60:61], v[120:121], v[2:3], v[60:61]
	v_lshlrev_b32_e32 v2, 16, v177
	v_and_b32_e32 v3, 0xffff0000, v177
	v_readlane_b32 s45, v254, 54
	s_movk_i32 s36, 0x6000
	s_and_b64 vcc, exec, s[40:41]
	v_pk_fma_f32 v[62:63], v[122:123], v[2:3], v[62:63]
	s_cbranch_vccnz .LBB0_1135
	s_add_u32 s14, s30, s6
	s_addc_u32 s15, s31, s7
	v_cvt_pk_bf16_f32 v2, v60, v61
	v_lshl_add_u64 v[60:61], s[14:15], 0, v[178:179]
	v_lshl_add_u64 v[60:61], v[140:141], 1, v[60:61]
	v_add_co_u32_e32 v60, vcc, 0x363ed000, v60
	v_cvt_pk_bf16_f32 v3, v62, v63
	s_nop 0
	v_addc_co_u32_e32 v61, vcc, 0, v61, vcc
	global_store_dwordx2 v[60:61], v[2:3], off offset:64
	v_mov_b32_e32 v2, v1
	v_mov_b32_e32 v3, v1
	v_mov_b32_e32 v0, v1
	v_mov_b64_e32 v[62:63], v[2:3]
	v_mov_b64_e32 v[60:61], v[0:1]
.LBB0_1135:
	s_waitcnt vmcnt(12)
	v_lshlrev_b32_e32 v2, 16, v174
	v_and_b32_e32 v3, 0xffff0000, v174
	v_pk_fma_f32 v[56:57], v[116:117], v[2:3], v[56:57]
	v_lshlrev_b32_e32 v2, 16, v175
	v_and_b32_e32 v3, 0xffff0000, v175
	s_and_b64 vcc, exec, s[40:41]
	v_pk_fma_f32 v[58:59], v[118:119], v[2:3], v[58:59]
	s_cbranch_vccnz .LBB0_1137
	s_add_u32 s14, s30, s6
	s_addc_u32 s15, s31, s7
	v_cvt_pk_bf16_f32 v2, v56, v57
	v_lshl_add_u64 v[56:57], s[14:15], 0, v[178:179]
	v_lshl_add_u64 v[56:57], v[140:141], 1, v[56:57]
	v_add_co_u32_e32 v56, vcc, 0x363ed000, v56
	v_cvt_pk_bf16_f32 v3, v58, v59
	s_nop 0
	v_addc_co_u32_e32 v57, vcc, 0, v57, vcc
	global_store_dwordx2 v[56:57], v[2:3], off offset:96
	v_mov_b32_e32 v2, v1
	v_mov_b32_e32 v3, v1
	v_mov_b32_e32 v0, v1
	v_mov_b64_e32 v[58:59], v[2:3]
	v_mov_b64_e32 v[56:57], v[0:1]
.LBB0_1137:
	s_waitcnt vmcnt(11)
	v_lshlrev_b32_e32 v2, 16, v172
	v_and_b32_e32 v3, 0xffff0000, v172
	v_pk_fma_f32 v[12:13], v[112:113], v[2:3], v[12:13]
	v_lshlrev_b32_e32 v2, 16, v173
	v_and_b32_e32 v3, 0xffff0000, v173
	v_lshlrev_b64 v[116:117], 12, v[170:171]
	s_and_b64 vcc, exec, s[40:41]
	v_pk_fma_f32 v[14:15], v[114:115], v[2:3], v[14:15]
	s_cbranch_vccnz .LBB0_1139
	s_add_u32 s14, s12, s6
	s_addc_u32 s15, s20, s7
	v_cvt_pk_bf16_f32 v2, v12, v13
	v_lshl_add_u64 v[12:13], s[14:15], 0, v[116:117]
	v_cvt_pk_bf16_f32 v3, v14, v15
	v_lshl_add_u64 v[12:13], v[140:141], 1, v[12:13]
	global_store_dwordx2 v[12:13], v[2:3], off
	v_mov_b32_e32 v2, v1
	v_mov_b32_e32 v3, v1
	v_mov_b32_e32 v0, v1
	v_mov_b64_e32 v[14:15], v[2:3]
	v_mov_b64_e32 v[12:13], v[0:1]
.LBB0_1139:
	s_waitcnt vmcnt(10)
	v_lshlrev_b32_e32 v2, 16, v168
	v_and_b32_e32 v3, 0xffff0000, v168
	v_pk_fma_f32 v[52:53], v[108:109], v[2:3], v[52:53]
	v_lshlrev_b32_e32 v2, 16, v169
	v_and_b32_e32 v3, 0xffff0000, v169
	s_and_b64 vcc, exec, s[40:41]
	v_pk_fma_f32 v[54:55], v[110:111], v[2:3], v[54:55]
	s_cbranch_vccnz .LBB0_1141
	s_add_u32 s14, s30, s6
	s_addc_u32 s15, s31, s7
	v_cvt_pk_bf16_f32 v2, v52, v53
	v_lshl_add_u64 v[52:53], s[14:15], 0, v[116:117]
	v_lshl_add_u64 v[52:53], v[140:141], 1, v[52:53]
	v_add_co_u32_e32 v52, vcc, 0x363ed000, v52
	v_cvt_pk_bf16_f32 v3, v54, v55
	s_nop 0
	v_addc_co_u32_e32 v53, vcc, 0, v53, vcc
	global_store_dwordx2 v[52:53], v[2:3], off offset:32
	v_mov_b32_e32 v2, v1
	v_mov_b32_e32 v3, v1
	v_mov_b32_e32 v0, v1
	v_mov_b64_e32 v[54:55], v[2:3]
	v_mov_b64_e32 v[52:53], v[0:1]
.LBB0_1141:
	s_waitcnt vmcnt(9)
	v_lshlrev_b32_e32 v2, 16, v166
	v_and_b32_e32 v3, 0xffff0000, v166
	v_pk_fma_f32 v[48:49], v[104:105], v[2:3], v[48:49]
	v_lshlrev_b32_e32 v2, 16, v167
	v_and_b32_e32 v3, 0xffff0000, v167
	s_and_b64 vcc, exec, s[40:41]
	v_pk_fma_f32 v[50:51], v[106:107], v[2:3], v[50:51]
	s_cbranch_vccnz .LBB0_1143
	s_add_u32 s14, s30, s6
	s_addc_u32 s15, s31, s7
	v_cvt_pk_bf16_f32 v2, v48, v49
	v_lshl_add_u64 v[48:49], s[14:15], 0, v[116:117]
	v_lshl_add_u64 v[48:49], v[140:141], 1, v[48:49]
	v_add_co_u32_e32 v48, vcc, 0x363ed000, v48
	v_cvt_pk_bf16_f32 v3, v50, v51
	s_nop 0
	v_addc_co_u32_e32 v49, vcc, 0, v49, vcc
	global_store_dwordx2 v[48:49], v[2:3], off offset:64
	v_mov_b32_e32 v2, v1
	v_mov_b32_e32 v3, v1
	v_mov_b32_e32 v0, v1
	v_mov_b64_e32 v[50:51], v[2:3]
	v_mov_b64_e32 v[48:49], v[0:1]
.LBB0_1143:
	s_waitcnt vmcnt(8)
	v_lshlrev_b32_e32 v2, 16, v164
	v_and_b32_e32 v3, 0xffff0000, v164
	v_pk_fma_f32 v[44:45], v[100:101], v[2:3], v[44:45]
	v_lshlrev_b32_e32 v2, 16, v165
	v_and_b32_e32 v3, 0xffff0000, v165
	s_and_b64 vcc, exec, s[40:41]
	v_pk_fma_f32 v[46:47], v[102:103], v[2:3], v[46:47]
	s_cbranch_vccnz .LBB0_1145
	s_add_u32 s14, s30, s6
	s_addc_u32 s15, s31, s7
	v_cvt_pk_bf16_f32 v2, v44, v45
	v_lshl_add_u64 v[44:45], s[14:15], 0, v[116:117]
	v_lshl_add_u64 v[44:45], v[140:141], 1, v[44:45]
	v_add_co_u32_e32 v44, vcc, 0x363ed000, v44
	v_cvt_pk_bf16_f32 v3, v46, v47
	s_nop 0
	v_addc_co_u32_e32 v45, vcc, 0, v45, vcc
	global_store_dwordx2 v[44:45], v[2:3], off offset:96
	v_mov_b32_e32 v2, v1
	v_mov_b32_e32 v3, v1
	v_mov_b32_e32 v0, v1
	v_mov_b64_e32 v[46:47], v[2:3]
	v_mov_b64_e32 v[44:45], v[0:1]
.LBB0_1145:
	s_waitcnt vmcnt(7)
	v_lshlrev_b32_e32 v2, 16, v162
	v_and_b32_e32 v3, 0xffff0000, v162
	v_pk_fma_f32 v[8:9], v[96:97], v[2:3], v[8:9]
	v_lshlrev_b32_e32 v2, 16, v163
	v_and_b32_e32 v3, 0xffff0000, v163
	v_lshlrev_b64 v[100:101], 12, v[160:161]
	s_and_b64 vcc, exec, s[40:41]
	v_pk_fma_f32 v[10:11], v[98:99], v[2:3], v[10:11]
	s_cbranch_vccnz .LBB0_1147
	s_add_u32 s14, s12, s6
	s_addc_u32 s15, s20, s7
	v_cvt_pk_bf16_f32 v2, v8, v9
	v_lshl_add_u64 v[8:9], s[14:15], 0, v[100:101]
	v_cvt_pk_bf16_f32 v3, v10, v11
	v_lshl_add_u64 v[8:9], v[140:141], 1, v[8:9]
	global_store_dwordx2 v[8:9], v[2:3], off
	v_mov_b32_e32 v2, v1
	v_mov_b32_e32 v3, v1
	v_mov_b32_e32 v0, v1
	v_mov_b64_e32 v[10:11], v[2:3]
	v_mov_b64_e32 v[8:9], v[0:1]
.LBB0_1147:
	s_waitcnt vmcnt(6)
	v_lshlrev_b32_e32 v2, 16, v158
	v_and_b32_e32 v3, 0xffff0000, v158
	v_pk_fma_f32 v[40:41], v[92:93], v[2:3], v[40:41]
	v_lshlrev_b32_e32 v2, 16, v159
	v_and_b32_e32 v3, 0xffff0000, v159
	s_and_b64 vcc, exec, s[40:41]
	v_pk_fma_f32 v[42:43], v[94:95], v[2:3], v[42:43]
	s_cbranch_vccnz .LBB0_1149
	s_add_u32 s14, s30, s6
	s_addc_u32 s15, s31, s7
	v_cvt_pk_bf16_f32 v2, v40, v41
	v_lshl_add_u64 v[40:41], s[14:15], 0, v[100:101]
	v_lshl_add_u64 v[40:41], v[140:141], 1, v[40:41]
	v_add_co_u32_e32 v40, vcc, 0x363ed000, v40
	v_cvt_pk_bf16_f32 v3, v42, v43
	s_nop 0
	v_addc_co_u32_e32 v41, vcc, 0, v41, vcc
	global_store_dwordx2 v[40:41], v[2:3], off offset:32
	v_mov_b32_e32 v2, v1
	v_mov_b32_e32 v3, v1
	v_mov_b32_e32 v0, v1
	v_mov_b64_e32 v[42:43], v[2:3]
	v_mov_b64_e32 v[40:41], v[0:1]
.LBB0_1149:
	s_waitcnt vmcnt(5)
	v_lshlrev_b32_e32 v2, 16, v156
	v_and_b32_e32 v3, 0xffff0000, v156
	v_pk_fma_f32 v[36:37], v[88:89], v[2:3], v[36:37]
	v_lshlrev_b32_e32 v2, 16, v157
	v_and_b32_e32 v3, 0xffff0000, v157
	s_and_b64 vcc, exec, s[40:41]
	v_pk_fma_f32 v[38:39], v[90:91], v[2:3], v[38:39]
	s_cbranch_vccnz .LBB0_1151
	s_add_u32 s14, s30, s6
	s_addc_u32 s15, s31, s7
	v_cvt_pk_bf16_f32 v2, v36, v37
	v_lshl_add_u64 v[36:37], s[14:15], 0, v[100:101]
	v_lshl_add_u64 v[36:37], v[140:141], 1, v[36:37]
	v_add_co_u32_e32 v36, vcc, 0x363ed000, v36
	v_cvt_pk_bf16_f32 v3, v38, v39
	s_nop 0
	v_addc_co_u32_e32 v37, vcc, 0, v37, vcc
	global_store_dwordx2 v[36:37], v[2:3], off offset:64
	v_mov_b32_e32 v2, v1
	v_mov_b32_e32 v3, v1
	v_mov_b32_e32 v0, v1
	v_mov_b64_e32 v[38:39], v[2:3]
	v_mov_b64_e32 v[36:37], v[0:1]
.LBB0_1151:
	s_waitcnt vmcnt(4)
	v_lshlrev_b32_e32 v2, 16, v154
	v_and_b32_e32 v3, 0xffff0000, v154
	v_pk_fma_f32 v[32:33], v[84:85], v[2:3], v[32:33]
	v_lshlrev_b32_e32 v2, 16, v155
	v_and_b32_e32 v3, 0xffff0000, v155
	s_and_b64 vcc, exec, s[40:41]
	v_pk_fma_f32 v[34:35], v[86:87], v[2:3], v[34:35]
	s_cbranch_vccnz .LBB0_1153
	s_add_u32 s14, s30, s6
	s_addc_u32 s15, s31, s7
	v_cvt_pk_bf16_f32 v2, v32, v33
	v_lshl_add_u64 v[32:33], s[14:15], 0, v[100:101]
	v_lshl_add_u64 v[32:33], v[140:141], 1, v[32:33]
	v_add_co_u32_e32 v32, vcc, 0x363ed000, v32
	v_cvt_pk_bf16_f32 v3, v34, v35
	s_nop 0
	v_addc_co_u32_e32 v33, vcc, 0, v33, vcc
	global_store_dwordx2 v[32:33], v[2:3], off offset:96
	v_mov_b32_e32 v2, v1
	v_mov_b32_e32 v3, v1
	v_mov_b32_e32 v0, v1
	v_mov_b64_e32 v[34:35], v[2:3]
	v_mov_b64_e32 v[32:33], v[0:1]
.LBB0_1153:
	s_waitcnt vmcnt(3)
	v_lshlrev_b32_e32 v2, 16, v152
	v_and_b32_e32 v3, 0xffff0000, v152
	v_pk_fma_f32 v[4:5], v[80:81], v[2:3], v[4:5]
	v_lshlrev_b32_e32 v2, 16, v153
	v_and_b32_e32 v3, 0xffff0000, v153
	v_lshlrev_b64 v[84:85], 12, v[148:149]
	s_and_b64 vcc, exec, s[40:41]
	v_pk_fma_f32 v[6:7], v[82:83], v[2:3], v[6:7]
	s_cbranch_vccnz .LBB0_1155
	s_add_u32 s14, s12, s6
	s_addc_u32 s15, s20, s7
	v_cvt_pk_bf16_f32 v2, v4, v5
	v_lshl_add_u64 v[4:5], s[14:15], 0, v[84:85]
	v_cvt_pk_bf16_f32 v3, v6, v7
	v_lshl_add_u64 v[4:5], v[140:141], 1, v[4:5]
	global_store_dwordx2 v[4:5], v[2:3], off
	v_mov_b32_e32 v2, v1
	v_mov_b32_e32 v3, v1
	v_mov_b32_e32 v0, v1
	v_mov_b64_e32 v[6:7], v[2:3]
	v_mov_b64_e32 v[4:5], v[0:1]
.LBB0_1155:
	s_waitcnt vmcnt(2)
	v_lshlrev_b32_e32 v2, 16, v146
	v_and_b32_e32 v3, 0xffff0000, v146
	v_pk_fma_f32 v[24:25], v[76:77], v[2:3], v[24:25]
	v_lshlrev_b32_e32 v2, 16, v147
	v_and_b32_e32 v3, 0xffff0000, v147
	s_and_b64 vcc, exec, s[40:41]
	v_pk_fma_f32 v[26:27], v[78:79], v[2:3], v[26:27]
	s_cbranch_vccnz .LBB0_1157
	s_add_u32 s14, s30, s6
	s_addc_u32 s15, s31, s7
	v_cvt_pk_bf16_f32 v2, v24, v25
	v_lshl_add_u64 v[24:25], s[14:15], 0, v[84:85]
	v_lshl_add_u64 v[24:25], v[140:141], 1, v[24:25]
	v_add_co_u32_e32 v24, vcc, 0x363ed000, v24
	v_cvt_pk_bf16_f32 v3, v26, v27
	s_nop 0
	v_addc_co_u32_e32 v25, vcc, 0, v25, vcc
	global_store_dwordx2 v[24:25], v[2:3], off offset:32
	v_mov_b32_e32 v2, v1
	v_mov_b32_e32 v3, v1
	v_mov_b32_e32 v0, v1
	v_mov_b64_e32 v[26:27], v[2:3]
	v_mov_b64_e32 v[24:25], v[0:1]
.LBB0_1157:
	s_waitcnt vmcnt(1)
	v_lshlrev_b32_e32 v2, 16, v144
	v_and_b32_e32 v3, 0xffff0000, v144
	v_pk_fma_f32 v[20:21], v[72:73], v[2:3], v[20:21]
	v_lshlrev_b32_e32 v2, 16, v145
	v_and_b32_e32 v3, 0xffff0000, v145
	s_and_b64 vcc, exec, s[40:41]
	v_pk_fma_f32 v[22:23], v[74:75], v[2:3], v[22:23]
	s_cbranch_vccnz .LBB0_1159
	s_add_u32 s14, s30, s6
	s_addc_u32 s15, s31, s7
	v_cvt_pk_bf16_f32 v2, v20, v21
	v_lshl_add_u64 v[20:21], s[14:15], 0, v[84:85]
	v_lshl_add_u64 v[20:21], v[140:141], 1, v[20:21]
	v_add_co_u32_e32 v20, vcc, 0x363ed000, v20
	v_cvt_pk_bf16_f32 v3, v22, v23
	s_nop 0
	v_addc_co_u32_e32 v21, vcc, 0, v21, vcc
	global_store_dwordx2 v[20:21], v[2:3], off offset:64
	v_mov_b32_e32 v2, v1
	v_mov_b32_e32 v3, v1
	v_mov_b32_e32 v0, v1
	v_mov_b64_e32 v[22:23], v[2:3]
	v_mov_b64_e32 v[20:21], v[0:1]
.LBB0_1159:
	s_waitcnt vmcnt(0)
	v_lshlrev_b32_e32 v2, 16, v142
	v_and_b32_e32 v3, 0xffff0000, v142
	v_pk_fma_f32 v[16:17], v[68:69], v[2:3], v[16:17]
	v_lshlrev_b32_e32 v2, 16, v143
	v_and_b32_e32 v3, 0xffff0000, v143
	s_and_b64 vcc, exec, s[40:41]
	v_pk_fma_f32 v[18:19], v[70:71], v[2:3], v[18:19]
	s_cbranch_vccnz .LBB0_1161
	s_add_u32 s6, s30, s6
	s_addc_u32 s7, s31, s7
	v_cvt_pk_bf16_f32 v2, v16, v17
	v_lshl_add_u64 v[16:17], s[6:7], 0, v[84:85]
	v_lshl_add_u64 v[16:17], v[140:141], 1, v[16:17]
	v_add_co_u32_e32 v16, vcc, 0x363ed000, v16
	v_cvt_pk_bf16_f32 v3, v18, v19
	s_nop 0
	v_addc_co_u32_e32 v17, vcc, 0, v17, vcc
	global_store_dwordx2 v[16:17], v[2:3], off offset:96
	v_mov_b32_e32 v2, v1
	v_mov_b32_e32 v3, v1
	v_mov_b32_e32 v0, v1
	v_mov_b64_e32 v[18:19], v[2:3]
	v_mov_b64_e32 v[16:17], v[0:1]
